# grid barrier: non-leader workgroups wait on the cross-XCC generation word, per-XCC generation bump removed
# speedup vs baseline: 1.0039x; 1.0039x over previous
; __device__ __forceinline__ unsigned xb_ld(unsigned* p)              { return __hip_atomic_load(p, __ATOMIC_RELAXED, __HIP_MEMORY_SCOPE_AGENT); }
; __device__ __forceinline__ unsigned xb_add(unsigned* p, unsigned v) { return __hip_atomic_fetch_add(p, v, __ATOMIC_RELAXED, __HIP_MEMORY_SCOPE_AGENT); }
; #define XB_SPIN(cond, bar) do { unsigned _sp = 0; while (cond) { __builtin_amdgcn_s_sleep(1); \
;     if ((++_sp & 255u) == 0u) { if (xb_ld(&(bar)[XB_TMO])) break; if (_sp > XB_SPIN_CAP) { atomicAdd(&(bar)[XB_TMO], 1u); break; } } } } while (0)
; __device__ __forceinline__ void gsync(const int wvs, LAS unsigned char* lds) {
;     ...
;     unsigned nloc = st[0], nx = st[1];
;     if (nloc == 0u) { xcd_complete(bar, x, nloc, nx); st[0] = nloc; st[1] = nx; }
;     const unsigned old = xb_add(&bar[XB_XSUB(x)], 1u);
;     const unsigned gen = old / nloc;
;     if (old + 1u == (gen + 1u) * nloc) {
;       __builtin_amdgcn_fence(__ATOMIC_RELEASE, "agent");
;       asm volatile("s_waitcnt vmcnt(0)" ::: "memory");
;       const unsigned og = xb_add(&bar[XB_TOP], 1u);
;       const unsigned tg = og / nx;
;       if (og + 1u == (tg + 1u) * nx) xb_add(&bar[XB_TOPGEN], 1u);
;       else XB_SPIN(xb_ld(&bar[XB_TOPGEN]) == tg, bar);
;       __builtin_amdgcn_fence(__ATOMIC_ACQUIRE, "agent");
;       xb_add(&bar[XB_XGEN(x)], 1u);
;       asm volatile("s_waitcnt vmcnt(0)" ::: "memory");
;     } else {
;       XB_SPIN(xb_ld(&bar[XB_XGEN(x)]) == gen, bar);
.LBB0_314:
	s_or_b64 exec, exec, s[10:11]
	v_cvt_f32_u32_e32 v4, v2
	s_waitcnt vmcnt(0)
	v_readfirstlane_b32 s8, v3
	v_sub_u32_e32 v3, 0, v2
	v_rcp_iflag_f32_e32 v4, v4
	v_add_u32_e32 v5, s8, v1
	v_mul_f32_e32 v4, 0x4f7ffffe, v4
	v_cvt_u32_f32_e32 v4, v4
	v_mul_lo_u32 v1, v3, v4
	v_mul_hi_u32 v1, v4, v1
	v_add_u32_e32 v1, v4, v1
	v_mul_hi_u32 v1, v5, v1
	v_mul_lo_u32 v3, v1, v2
	v_sub_u32_e32 v3, v5, v3
	v_add_u32_e32 v4, 1, v1
	v_cmp_ge_u32_e32 vcc, v3, v2
	s_nop 1
	v_cndmask_b32_e32 v1, v1, v4, vcc
	v_sub_u32_e32 v4, v3, v2
	v_cndmask_b32_e32 v3, v3, v4, vcc
	v_add_u32_e32 v4, 1, v1
	v_cmp_ge_u32_e32 vcc, v3, v2
	v_add_u32_e32 v3, 1, v5
	s_nop 0
	v_cndmask_b32_e32 v1, v1, v4, vcc
	v_mul_lo_u32 v4, v2, v1
	v_add_u32_e32 v2, v4, v2
	v_cmp_ne_u32_e32 vcc, v3, v2
	s_and_saveexec_b64 s[8:9], vcc
	s_xor_b64 s[8:9], exec, s[8:9]
	s_cbranch_execz .LBB0_328
	s_waitcnt lgkmcnt(0)
	v_mov_b32_e32 v0, 0x2000
	s_add_u32 s14, s4, 0xffff500
	s_addc_u32 s15, s5, 0
	v_mov_b32_e32 v0, 0
	global_load_dword v0, v0, s[14:15] sc1
	s_waitcnt vmcnt(0)
	v_cmp_eq_u32_e32 vcc, v0, v1
	s_and_saveexec_b64 s[10:11], vcc
	s_cbranch_execz .LBB0_327
	s_add_u32 s12, s4, 0xfffc200
	s_addc_u32 s13, s5, 0
	s_mov_b32 s26, 1
	s_mov_b64 s[16:17], 0
	v_mov_b32_e32 v0, 0
	s_branch .LBB0_318

; __device__ __forceinline__ unsigned xb_ld(unsigned* p)              { return __hip_atomic_load(p, __ATOMIC_RELAXED, __HIP_MEMORY_SCOPE_AGENT); }
; __device__ __forceinline__ unsigned xb_add(unsigned* p, unsigned v) { return __hip_atomic_fetch_add(p, v, __ATOMIC_RELAXED, __HIP_MEMORY_SCOPE_AGENT); }
; #define XB_SPIN(cond, bar) do { unsigned _sp = 0; while (cond) { __builtin_amdgcn_s_sleep(1); \
;     if ((++_sp & 255u) == 0u) { if (xb_ld(&(bar)[XB_TMO])) break; if (_sp > XB_SPIN_CAP) { atomicAdd(&(bar)[XB_TMO], 1u); break; } } } } while (0)
; __device__ __forceinline__ void gsync(const int wvs, LAS unsigned char* lds) {
;     ...
;     if (old + 1u == (gen + 1u) * nloc) {
;       __builtin_amdgcn_fence(__ATOMIC_RELEASE, "agent");
;       asm volatile("s_waitcnt vmcnt(0)" ::: "memory");
;       const unsigned og = xb_add(&bar[XB_TOP], 1u);
;       const unsigned tg = og / nx;
;       if (og + 1u == (tg + 1u) * nx) xb_add(&bar[XB_TOPGEN], 1u);
;       else XB_SPIN(xb_ld(&bar[XB_TOPGEN]) == tg, bar);
;       __builtin_amdgcn_fence(__ATOMIC_ACQUIRE, "agent");
;       xb_add(&bar[XB_XGEN(x)], 1u);
;       asm volatile("s_waitcnt vmcnt(0)" ::: "memory");
.LBB0_345:
	s_or_b64 exec, exec, s[4:5]
	s_mov_b64 s[4:5], exec
	v_mbcnt_lo_u32_b32 v0, s4, 0
	v_mbcnt_hi_u32_b32 v0, s5, v0
	v_cmp_eq_u32_e32 vcc, 0, v0
	s_waitcnt vmcnt(0)
	buffer_inv sc1
	s_and_saveexec_b64 s[8:9], vcc
	s_cbranch_execz .LBB0_347
	s_bcnt1_i32_b64 s4, s[4:5]
	v_mov_b32_e32 v0, 0x2000
	v_mov_b32_e32 v1, s4
.LBB0_347:
	s_or_b64 exec, exec, s[8:9]
	s_waitcnt vmcnt(0)

; __device__ __forceinline__ unsigned xb_ld(unsigned* p)              { return __hip_atomic_load(p, __ATOMIC_RELAXED, __HIP_MEMORY_SCOPE_AGENT); }
; __device__ __forceinline__ unsigned xb_add(unsigned* p, unsigned v) { return __hip_atomic_fetch_add(p, v, __ATOMIC_RELAXED, __HIP_MEMORY_SCOPE_AGENT); }
; #define XB_SPIN(cond, bar) do { unsigned _sp = 0; while (cond) { __builtin_amdgcn_s_sleep(1); \
;     if ((++_sp & 255u) == 0u) { if (xb_ld(&(bar)[XB_TMO])) break; if (_sp > XB_SPIN_CAP) { atomicAdd(&(bar)[XB_TMO], 1u); break; } } } } while (0)
; __device__ __forceinline__ void gsync(const int wvs, LAS unsigned char* lds) {
;     ...
;     unsigned nloc = st[0], nx = st[1];
;     if (nloc == 0u) { xcd_complete(bar, x, nloc, nx); st[0] = nloc; st[1] = nx; }
;     const unsigned old = xb_add(&bar[XB_XSUB(x)], 1u);
;     const unsigned gen = old / nloc;
;     if (old + 1u == (gen + 1u) * nloc) {
;       __builtin_amdgcn_fence(__ATOMIC_RELEASE, "agent");
;       asm volatile("s_waitcnt vmcnt(0)" ::: "memory");
;       const unsigned og = xb_add(&bar[XB_TOP], 1u);
;       const unsigned tg = og / nx;
;       if (og + 1u == (tg + 1u) * nx) xb_add(&bar[XB_TOPGEN], 1u);
;       else XB_SPIN(xb_ld(&bar[XB_TOPGEN]) == tg, bar);
;       __builtin_amdgcn_fence(__ATOMIC_ACQUIRE, "agent");
;       xb_add(&bar[XB_XGEN(x)], 1u);
;       asm volatile("s_waitcnt vmcnt(0)" ::: "memory");
;     } else {
;       XB_SPIN(xb_ld(&bar[XB_XGEN(x)]) == gen, bar);
.LBB0_552:
	s_or_b64 exec, exec, s[12:13]
	v_cvt_f32_u32_e32 v5, v3
	s_waitcnt vmcnt(0)
	v_readfirstlane_b32 s2, v4
	v_sub_u32_e32 v4, 0, v3
	v_rcp_iflag_f32_e32 v5, v5
	v_add_u32_e32 v6, s2, v0
	v_mul_f32_e32 v5, 0x4f7ffffe, v5
	v_cvt_u32_f32_e32 v5, v5
	v_mul_lo_u32 v0, v4, v5
	v_mul_hi_u32 v0, v5, v0
	v_add_u32_e32 v0, v5, v0
	v_mul_hi_u32 v0, v6, v0
	v_mul_lo_u32 v4, v0, v3
	v_sub_u32_e32 v4, v6, v4
	v_add_u32_e32 v5, 1, v0
	v_cmp_ge_u32_e32 vcc, v4, v3
	s_nop 1
	v_cndmask_b32_e32 v0, v0, v5, vcc
	v_sub_u32_e32 v5, v4, v3
	v_cndmask_b32_e32 v4, v4, v5, vcc
	v_add_u32_e32 v5, 1, v0
	v_cmp_ge_u32_e32 vcc, v4, v3
	v_add_u32_e32 v4, 1, v6
	s_nop 0
	v_cndmask_b32_e32 v0, v0, v5, vcc
	v_mul_lo_u32 v5, v3, v0
	v_add_u32_e32 v3, v5, v3
	v_cmp_ne_u32_e32 vcc, v4, v3
	s_and_saveexec_b64 s[2:3], vcc
	s_xor_b64 s[10:11], exec, s[2:3]
	s_cbranch_execz .LBB0_566
	s_waitcnt lgkmcnt(0)
	s_add_u32 s16, s6, 0xffff500
	s_addc_u32 s17, s7, 0
	v_mov_b32_e32 v2, 0
	global_load_dword v2, v2, s[16:17] sc1
	s_waitcnt vmcnt(0)
	v_cmp_eq_u32_e32 vcc, v2, v0
	s_and_saveexec_b64 s[12:13], vcc
	s_cbranch_execz .LBB0_565
	s_add_u32 s14, s6, 0xfffc200
	s_addc_u32 s15, s7, 0
	s_mov_b32 s2, 1
	s_mov_b64 s[18:19], 0
	s_branch .LBB0_556

; __device__ __forceinline__ unsigned xb_ld(unsigned* p)              { return __hip_atomic_load(p, __ATOMIC_RELAXED, __HIP_MEMORY_SCOPE_AGENT); }
; __device__ __forceinline__ unsigned xb_add(unsigned* p, unsigned v) { return __hip_atomic_fetch_add(p, v, __ATOMIC_RELAXED, __HIP_MEMORY_SCOPE_AGENT); }
; #define XB_SPIN(cond, bar) do { unsigned _sp = 0; while (cond) { __builtin_amdgcn_s_sleep(1); \
;     if ((++_sp & 255u) == 0u) { if (xb_ld(&(bar)[XB_TMO])) break; if (_sp > XB_SPIN_CAP) { atomicAdd(&(bar)[XB_TMO], 1u); break; } } } } while (0)
; __device__ __forceinline__ void gsync(const int wvs, LAS unsigned char* lds) {
;     ...
;     if (old + 1u == (gen + 1u) * nloc) {
;       __builtin_amdgcn_fence(__ATOMIC_RELEASE, "agent");
;       asm volatile("s_waitcnt vmcnt(0)" ::: "memory");
;       const unsigned og = xb_add(&bar[XB_TOP], 1u);
;       const unsigned tg = og / nx;
;       if (og + 1u == (tg + 1u) * nx) xb_add(&bar[XB_TOPGEN], 1u);
;       else XB_SPIN(xb_ld(&bar[XB_TOPGEN]) == tg, bar);
;       __builtin_amdgcn_fence(__ATOMIC_ACQUIRE, "agent");
;       xb_add(&bar[XB_XGEN(x)], 1u);
;       asm volatile("s_waitcnt vmcnt(0)" ::: "memory");
.LBB0_583:
	s_or_b64 exec, exec, s[6:7]
	s_mov_b64 s[6:7], exec
	v_mbcnt_lo_u32_b32 v0, s6, 0
	v_mbcnt_hi_u32_b32 v0, s7, v0
	v_cmp_eq_u32_e32 vcc, 0, v0
	s_waitcnt vmcnt(0)
	buffer_inv sc1
	s_and_saveexec_b64 s[10:11], vcc
	s_cbranch_execz .LBB0_585
	s_bcnt1_i32_b64 s2, s[6:7]
	v_mov_b32_e32 v0, s2
.LBB0_585:
	s_or_b64 exec, exec, s[10:11]
	s_waitcnt vmcnt(0)

; __device__ __forceinline__ unsigned xb_ld(unsigned* p)              { return __hip_atomic_load(p, __ATOMIC_RELAXED, __HIP_MEMORY_SCOPE_AGENT); }
; __device__ __forceinline__ unsigned xb_add(unsigned* p, unsigned v) { return __hip_atomic_fetch_add(p, v, __ATOMIC_RELAXED, __HIP_MEMORY_SCOPE_AGENT); }
; #define XB_SPIN(cond, bar) do { unsigned _sp = 0; while (cond) { __builtin_amdgcn_s_sleep(1); \
;     if ((++_sp & 255u) == 0u) { if (xb_ld(&(bar)[XB_TMO])) break; if (_sp > XB_SPIN_CAP) { atomicAdd(&(bar)[XB_TMO], 1u); break; } } } } while (0)
; __device__ __forceinline__ void gsync(const int wvs, LAS unsigned char* lds) {
;     ...
;     if (old + 1u == (gen + 1u) * nloc) {
;       __builtin_amdgcn_fence(__ATOMIC_RELEASE, "agent");
;       asm volatile("s_waitcnt vmcnt(0)" ::: "memory");
;       const unsigned og = xb_add(&bar[XB_TOP], 1u);
;       const unsigned tg = og / nx;
;       if (og + 1u == (tg + 1u) * nx) xb_add(&bar[XB_TOPGEN], 1u);
;       else XB_SPIN(xb_ld(&bar[XB_TOPGEN]) == tg, bar);
;       __builtin_amdgcn_fence(__ATOMIC_ACQUIRE, "agent");
;       xb_add(&bar[XB_XGEN(x)], 1u);
;       asm volatile("s_waitcnt vmcnt(0)" ::: "memory");
.LBB0_648:
	s_or_b64 exec, exec, s[6:7]
	s_mov_b64 s[6:7], exec
	v_mbcnt_lo_u32_b32 v0, s6, 0
	v_mbcnt_hi_u32_b32 v0, s7, v0
	v_cmp_eq_u32_e32 vcc, 0, v0
	s_waitcnt vmcnt(0)
	buffer_inv sc1
	s_and_saveexec_b64 s[10:11], vcc
	s_cbranch_execz .LBB0_650
	s_bcnt1_i32_b64 s2, s[6:7]
	v_mov_b32_e32 v0, s2
.LBB0_650:
	s_or_b64 exec, exec, s[10:11]
	s_waitcnt vmcnt(0)

; __device__ __forceinline__ unsigned xb_ld(unsigned* p)              { return __hip_atomic_load(p, __ATOMIC_RELAXED, __HIP_MEMORY_SCOPE_AGENT); }
; __device__ __forceinline__ unsigned xb_add(unsigned* p, unsigned v) { return __hip_atomic_fetch_add(p, v, __ATOMIC_RELAXED, __HIP_MEMORY_SCOPE_AGENT); }
; #define XB_SPIN(cond, bar) do { unsigned _sp = 0; while (cond) { __builtin_amdgcn_s_sleep(1); \
;     if ((++_sp & 255u) == 0u) { if (xb_ld(&(bar)[XB_TMO])) break; if (_sp > XB_SPIN_CAP) { atomicAdd(&(bar)[XB_TMO], 1u); break; } } } } while (0)
; __device__ __forceinline__ void gsync(const int wvs, LAS unsigned char* lds) {
;     ...
;     if (old + 1u == (gen + 1u) * nloc) {
;       __builtin_amdgcn_fence(__ATOMIC_RELEASE, "agent");
;       asm volatile("s_waitcnt vmcnt(0)" ::: "memory");
;       const unsigned og = xb_add(&bar[XB_TOP], 1u);
;       const unsigned tg = og / nx;
;       if (og + 1u == (tg + 1u) * nx) xb_add(&bar[XB_TOPGEN], 1u);
;       else XB_SPIN(xb_ld(&bar[XB_TOPGEN]) == tg, bar);
;       __builtin_amdgcn_fence(__ATOMIC_ACQUIRE, "agent");
;       xb_add(&bar[XB_XGEN(x)], 1u);
;       asm volatile("s_waitcnt vmcnt(0)" ::: "memory");
.LBB0_835:
	s_or_b64 exec, exec, s[6:7]
	s_mov_b64 s[6:7], exec
	v_mbcnt_lo_u32_b32 v0, s6, 0
	v_mbcnt_hi_u32_b32 v0, s7, v0
	v_cmp_eq_u32_e32 vcc, 0, v0
	s_waitcnt vmcnt(0)
	buffer_inv sc1
	s_and_saveexec_b64 s[10:11], vcc
	s_cbranch_execz .LBB0_837
	s_bcnt1_i32_b64 s2, s[6:7]
	v_mov_b32_e32 v0, s2
.LBB0_837:
	s_or_b64 exec, exec, s[10:11]
	s_waitcnt vmcnt(0)

; __device__ __forceinline__ unsigned xb_ld(unsigned* p)              { return __hip_atomic_load(p, __ATOMIC_RELAXED, __HIP_MEMORY_SCOPE_AGENT); }
; __device__ __forceinline__ unsigned xb_add(unsigned* p, unsigned v) { return __hip_atomic_fetch_add(p, v, __ATOMIC_RELAXED, __HIP_MEMORY_SCOPE_AGENT); }
; #define XB_SPIN(cond, bar) do { unsigned _sp = 0; while (cond) { __builtin_amdgcn_s_sleep(1); \
;     if ((++_sp & 255u) == 0u) { if (xb_ld(&(bar)[XB_TMO])) break; if (_sp > XB_SPIN_CAP) { atomicAdd(&(bar)[XB_TMO], 1u); break; } } } } while (0)
; __device__ __forceinline__ void gsync(const int wvs, LAS unsigned char* lds) {
;     ...
;     if (old + 1u == (gen + 1u) * nloc) {
;       __builtin_amdgcn_fence(__ATOMIC_RELEASE, "agent");
;       asm volatile("s_waitcnt vmcnt(0)" ::: "memory");
;       const unsigned og = xb_add(&bar[XB_TOP], 1u);
;       const unsigned tg = og / nx;
;       if (og + 1u == (tg + 1u) * nx) xb_add(&bar[XB_TOPGEN], 1u);
;       else XB_SPIN(xb_ld(&bar[XB_TOPGEN]) == tg, bar);
;       __builtin_amdgcn_fence(__ATOMIC_ACQUIRE, "agent");
;       xb_add(&bar[XB_XGEN(x)], 1u);
;       asm volatile("s_waitcnt vmcnt(0)" ::: "memory");
.LBB0_1140:
	s_or_b64 exec, exec, s[6:7]
	s_mov_b64 s[6:7], exec
	v_mbcnt_lo_u32_b32 v0, s6, 0
	v_mbcnt_hi_u32_b32 v0, s7, v0
	v_cmp_eq_u32_e32 vcc, 0, v0
	s_waitcnt vmcnt(0)
	buffer_inv sc1
	s_and_saveexec_b64 s[10:11], vcc
	s_cbranch_execz .LBB0_1142
	s_bcnt1_i32_b64 s2, s[6:7]
	v_mov_b32_e32 v0, s2
.LBB0_1142:
	s_or_b64 exec, exec, s[10:11]
	s_waitcnt vmcnt(0)

; __device__ __forceinline__ unsigned xb_ld(unsigned* p)              { return __hip_atomic_load(p, __ATOMIC_RELAXED, __HIP_MEMORY_SCOPE_AGENT); }
; __device__ __forceinline__ unsigned xb_add(unsigned* p, unsigned v) { return __hip_atomic_fetch_add(p, v, __ATOMIC_RELAXED, __HIP_MEMORY_SCOPE_AGENT); }
; #define XB_SPIN(cond, bar) do { unsigned _sp = 0; while (cond) { __builtin_amdgcn_s_sleep(1); \
;     if ((++_sp & 255u) == 0u) { if (xb_ld(&(bar)[XB_TMO])) break; if (_sp > XB_SPIN_CAP) { atomicAdd(&(bar)[XB_TMO], 1u); break; } } } } while (0)
; __device__ __forceinline__ void gsync(const int wvs, LAS unsigned char* lds) {
;     ...
;     unsigned nloc = st[0], nx = st[1];
;     if (nloc == 0u) { xcd_complete(bar, x, nloc, nx); st[0] = nloc; st[1] = nx; }
;     const unsigned old = xb_add(&bar[XB_XSUB(x)], 1u);
;     const unsigned gen = old / nloc;
;     if (old + 1u == (gen + 1u) * nloc) {
;       __builtin_amdgcn_fence(__ATOMIC_RELEASE, "agent");
;       asm volatile("s_waitcnt vmcnt(0)" ::: "memory");
;       const unsigned og = xb_add(&bar[XB_TOP], 1u);
;       const unsigned tg = og / nx;
;       if (og + 1u == (tg + 1u) * nx) xb_add(&bar[XB_TOPGEN], 1u);
;       else XB_SPIN(xb_ld(&bar[XB_TOPGEN]) == tg, bar);
;       __builtin_amdgcn_fence(__ATOMIC_ACQUIRE, "agent");
;       xb_add(&bar[XB_XGEN(x)], 1u);
;       asm volatile("s_waitcnt vmcnt(0)" ::: "memory");
;     } else {
;       XB_SPIN(xb_ld(&bar[XB_XGEN(x)]) == gen, bar);
.LBB0_1166:
	s_or_b64 exec, exec, s[12:13]
	v_cvt_f32_u32_e32 v5, v3
	s_waitcnt vmcnt(0)
	v_readfirstlane_b32 s2, v4
	v_sub_u32_e32 v4, 0, v3
	v_rcp_iflag_f32_e32 v5, v5
	v_add_u32_e32 v6, s2, v0
	v_mul_f32_e32 v5, 0x4f7ffffe, v5
	v_cvt_u32_f32_e32 v5, v5
	v_mul_lo_u32 v0, v4, v5
	v_mul_hi_u32 v0, v5, v0
	v_add_u32_e32 v0, v5, v0
	v_mul_hi_u32 v0, v6, v0
	v_mul_lo_u32 v4, v0, v3
	v_sub_u32_e32 v4, v6, v4
	v_add_u32_e32 v5, 1, v0
	v_cmp_ge_u32_e32 vcc, v4, v3
	s_nop 1
	v_cndmask_b32_e32 v0, v0, v5, vcc
	v_sub_u32_e32 v5, v4, v3
	v_cndmask_b32_e32 v4, v4, v5, vcc
	v_add_u32_e32 v5, 1, v0
	v_cmp_ge_u32_e32 vcc, v4, v3
	v_add_u32_e32 v4, 1, v6
	s_nop 0
	v_cndmask_b32_e32 v0, v0, v5, vcc
	v_mul_lo_u32 v5, v3, v0
	v_add_u32_e32 v3, v5, v3
	v_cmp_ne_u32_e32 vcc, v4, v3
	s_and_saveexec_b64 s[10:11], vcc
	s_xor_b64 s[10:11], exec, s[10:11]
	s_cbranch_execz .LBB0_1180
	s_waitcnt lgkmcnt(0)
	s_add_u32 s16, s6, 0xffff500
	s_addc_u32 s17, s7, 0
	v_mov_b32_e32 v2, 0
	global_load_dword v2, v2, s[16:17] sc1
	s_waitcnt vmcnt(0)
	v_cmp_eq_u32_e32 vcc, v2, v0
	s_and_saveexec_b64 s[12:13], vcc
	s_cbranch_execz .LBB0_1179
	s_add_u32 s14, s6, 0xfffc200
	s_addc_u32 s15, s7, 0
	s_mov_b32 s2, 1
	s_mov_b64 s[18:19], 0
	s_branch .LBB0_1170

; __device__ __forceinline__ unsigned xb_ld(unsigned* p)              { return __hip_atomic_load(p, __ATOMIC_RELAXED, __HIP_MEMORY_SCOPE_AGENT); }
; __device__ __forceinline__ unsigned xb_add(unsigned* p, unsigned v) { return __hip_atomic_fetch_add(p, v, __ATOMIC_RELAXED, __HIP_MEMORY_SCOPE_AGENT); }
; #define XB_SPIN(cond, bar) do { unsigned _sp = 0; while (cond) { __builtin_amdgcn_s_sleep(1); \
;     if ((++_sp & 255u) == 0u) { if (xb_ld(&(bar)[XB_TMO])) break; if (_sp > XB_SPIN_CAP) { atomicAdd(&(bar)[XB_TMO], 1u); break; } } } } while (0)
; __device__ __forceinline__ void gsync(const int wvs, LAS unsigned char* lds) {
;     ...
;     if (old + 1u == (gen + 1u) * nloc) {
;       __builtin_amdgcn_fence(__ATOMIC_RELEASE, "agent");
;       asm volatile("s_waitcnt vmcnt(0)" ::: "memory");
;       const unsigned og = xb_add(&bar[XB_TOP], 1u);
;       const unsigned tg = og / nx;
;       if (og + 1u == (tg + 1u) * nx) xb_add(&bar[XB_TOPGEN], 1u);
;       else XB_SPIN(xb_ld(&bar[XB_TOPGEN]) == tg, bar);
;       __builtin_amdgcn_fence(__ATOMIC_ACQUIRE, "agent");
;       xb_add(&bar[XB_XGEN(x)], 1u);
;       asm volatile("s_waitcnt vmcnt(0)" ::: "memory");
.LBB0_1197:
	s_or_b64 exec, exec, s[6:7]
	s_mov_b64 s[6:7], exec
	v_mbcnt_lo_u32_b32 v0, s6, 0
	v_mbcnt_hi_u32_b32 v0, s7, v0
	v_cmp_eq_u32_e32 vcc, 0, v0
	s_waitcnt vmcnt(0)
	buffer_inv sc1
	s_and_saveexec_b64 s[10:11], vcc
	s_cbranch_execz .LBB0_1199
	s_bcnt1_i32_b64 s2, s[6:7]
	v_mov_b32_e32 v0, s2
.LBB0_1199:
	s_or_b64 exec, exec, s[10:11]
	s_waitcnt vmcnt(0)

; __device__ __forceinline__ unsigned xb_ld(unsigned* p)              { return __hip_atomic_load(p, __ATOMIC_RELAXED, __HIP_MEMORY_SCOPE_AGENT); }
; __device__ __forceinline__ unsigned xb_add(unsigned* p, unsigned v) { return __hip_atomic_fetch_add(p, v, __ATOMIC_RELAXED, __HIP_MEMORY_SCOPE_AGENT); }
; #define XB_SPIN(cond, bar) do { unsigned _sp = 0; while (cond) { __builtin_amdgcn_s_sleep(1); \
;     if ((++_sp & 255u) == 0u) { if (xb_ld(&(bar)[XB_TMO])) break; if (_sp > XB_SPIN_CAP) { atomicAdd(&(bar)[XB_TMO], 1u); break; } } } } while (0)
; __device__ __forceinline__ void gsync(const int wvs, LAS unsigned char* lds) {
;     ...
;     if (old + 1u == (gen + 1u) * nloc) {
;       __builtin_amdgcn_fence(__ATOMIC_RELEASE, "agent");
;       asm volatile("s_waitcnt vmcnt(0)" ::: "memory");
;       const unsigned og = xb_add(&bar[XB_TOP], 1u);
;       const unsigned tg = og / nx;
;       if (og + 1u == (tg + 1u) * nx) xb_add(&bar[XB_TOPGEN], 1u);
;       else XB_SPIN(xb_ld(&bar[XB_TOPGEN]) == tg, bar);
;       __builtin_amdgcn_fence(__ATOMIC_ACQUIRE, "agent");
;       xb_add(&bar[XB_XGEN(x)], 1u);
;       asm volatile("s_waitcnt vmcnt(0)" ::: "memory");
.LBB0_1421:
	s_or_b64 exec, exec, s[6:7]
	s_mov_b64 s[6:7], exec
	v_mbcnt_lo_u32_b32 v0, s6, 0
	v_mbcnt_hi_u32_b32 v0, s7, v0
	v_cmp_eq_u32_e32 vcc, 0, v0
	s_waitcnt vmcnt(0)
	buffer_inv sc1
	s_and_saveexec_b64 s[10:11], vcc
	s_cbranch_execz .LBB0_1423
	s_bcnt1_i32_b64 s2, s[6:7]
	v_mov_b32_e32 v0, s2
.LBB0_1423:
	s_or_b64 exec, exec, s[10:11]
	s_waitcnt vmcnt(0)

; __device__ __forceinline__ unsigned xb_ld(unsigned* p)              { return __hip_atomic_load(p, __ATOMIC_RELAXED, __HIP_MEMORY_SCOPE_AGENT); }
; __device__ __forceinline__ unsigned xb_add(unsigned* p, unsigned v) { return __hip_atomic_fetch_add(p, v, __ATOMIC_RELAXED, __HIP_MEMORY_SCOPE_AGENT); }
; #define XB_SPIN(cond, bar) do { unsigned _sp = 0; while (cond) { __builtin_amdgcn_s_sleep(1); \
;     if ((++_sp & 255u) == 0u) { if (xb_ld(&(bar)[XB_TMO])) break; if (_sp > XB_SPIN_CAP) { atomicAdd(&(bar)[XB_TMO], 1u); break; } } } } while (0)
; __device__ __forceinline__ void gsync(const int wvs, LAS unsigned char* lds) {
;     ...
;     if (old + 1u == (gen + 1u) * nloc) {
;       __builtin_amdgcn_fence(__ATOMIC_RELEASE, "agent");
;       asm volatile("s_waitcnt vmcnt(0)" ::: "memory");
;       const unsigned og = xb_add(&bar[XB_TOP], 1u);
;       const unsigned tg = og / nx;
;       if (og + 1u == (tg + 1u) * nx) xb_add(&bar[XB_TOPGEN], 1u);
;       else XB_SPIN(xb_ld(&bar[XB_TOPGEN]) == tg, bar);
;       __builtin_amdgcn_fence(__ATOMIC_ACQUIRE, "agent");
;       xb_add(&bar[XB_XGEN(x)], 1u);
;       asm volatile("s_waitcnt vmcnt(0)" ::: "memory");
.LBB0_1485:
	s_or_b64 exec, exec, s[6:7]
	s_mov_b64 s[6:7], exec
	v_mbcnt_lo_u32_b32 v0, s6, 0
	v_mbcnt_hi_u32_b32 v0, s7, v0
	v_cmp_eq_u32_e32 vcc, 0, v0
	s_waitcnt vmcnt(0)
	buffer_inv sc1
	s_and_saveexec_b64 s[10:11], vcc
	s_cbranch_execz .LBB0_1487
	s_bcnt1_i32_b64 s2, s[6:7]
	v_mov_b32_e32 v0, s2
.LBB0_1487:
	s_or_b64 exec, exec, s[10:11]
	s_waitcnt vmcnt(0)

; __device__ __forceinline__ unsigned xb_ld(unsigned* p)              { return __hip_atomic_load(p, __ATOMIC_RELAXED, __HIP_MEMORY_SCOPE_AGENT); }
; __device__ __forceinline__ unsigned xb_add(unsigned* p, unsigned v) { return __hip_atomic_fetch_add(p, v, __ATOMIC_RELAXED, __HIP_MEMORY_SCOPE_AGENT); }
; #define XB_SPIN(cond, bar) do { unsigned _sp = 0; while (cond) { __builtin_amdgcn_s_sleep(1); \
;     if ((++_sp & 255u) == 0u) { if (xb_ld(&(bar)[XB_TMO])) break; if (_sp > XB_SPIN_CAP) { atomicAdd(&(bar)[XB_TMO], 1u); break; } } } } while (0)
; __device__ __forceinline__ void gsync(const int wvs, LAS unsigned char* lds) {
;     ...
;     unsigned nloc = st[0], nx = st[1];
;     if (nloc == 0u) { xcd_complete(bar, x, nloc, nx); st[0] = nloc; st[1] = nx; }
;     const unsigned old = xb_add(&bar[XB_XSUB(x)], 1u);
;     const unsigned gen = old / nloc;
;     if (old + 1u == (gen + 1u) * nloc) {
;       __builtin_amdgcn_fence(__ATOMIC_RELEASE, "agent");
;       asm volatile("s_waitcnt vmcnt(0)" ::: "memory");
;       const unsigned og = xb_add(&bar[XB_TOP], 1u);
;       const unsigned tg = og / nx;
;       if (og + 1u == (tg + 1u) * nx) xb_add(&bar[XB_TOPGEN], 1u);
;       else XB_SPIN(xb_ld(&bar[XB_TOPGEN]) == tg, bar);
;       __builtin_amdgcn_fence(__ATOMIC_ACQUIRE, "agent");
;       xb_add(&bar[XB_XGEN(x)], 1u);
;       asm volatile("s_waitcnt vmcnt(0)" ::: "memory");
;     } else {
;       XB_SPIN(xb_ld(&bar[XB_XGEN(x)]) == gen, bar);
.LBB0_1547:
	s_or_b64 exec, exec, s[14:15]
	v_cvt_f32_u32_e32 v5, v3
	s_waitcnt vmcnt(0)
	v_readfirstlane_b32 s2, v4
	v_sub_u32_e32 v4, 0, v3
	v_rcp_iflag_f32_e32 v5, v5
	v_add_u32_e32 v6, s2, v0
	v_mul_f32_e32 v5, 0x4f7ffffe, v5
	v_cvt_u32_f32_e32 v5, v5
	v_mul_lo_u32 v0, v4, v5
	v_mul_hi_u32 v0, v5, v0
	v_add_u32_e32 v0, v5, v0
	v_mul_hi_u32 v0, v6, v0
	v_mul_lo_u32 v4, v0, v3
	v_sub_u32_e32 v4, v6, v4
	v_add_u32_e32 v5, 1, v0
	v_cmp_ge_u32_e32 vcc, v4, v3
	s_nop 1
	v_cndmask_b32_e32 v0, v0, v5, vcc
	v_sub_u32_e32 v5, v4, v3
	v_cndmask_b32_e32 v4, v4, v5, vcc
	v_add_u32_e32 v5, 1, v0
	v_cmp_ge_u32_e32 vcc, v4, v3
	v_add_u32_e32 v4, 1, v6
	s_nop 0
	v_cndmask_b32_e32 v0, v0, v5, vcc
	v_mul_lo_u32 v5, v3, v0
	v_add_u32_e32 v3, v5, v3
	v_cmp_ne_u32_e32 vcc, v4, v3
	s_and_saveexec_b64 s[2:3], vcc
	s_xor_b64 s[12:13], exec, s[2:3]
	s_cbranch_execz .LBB0_1561
	s_waitcnt lgkmcnt(0)
	s_add_u32 s18, s8, 0xffff500
	s_addc_u32 s19, s9, 0
	v_mov_b32_e32 v2, 0
	global_load_dword v2, v2, s[18:19] sc1
	s_waitcnt vmcnt(0)
	v_cmp_eq_u32_e32 vcc, v2, v0
	s_and_saveexec_b64 s[14:15], vcc
	s_cbranch_execz .LBB0_1560
	s_add_u32 s16, s8, 0xfffc200
	s_addc_u32 s17, s9, 0
	s_mov_b32 s2, 1
	s_mov_b64 s[20:21], 0
	s_branch .LBB0_1551

; __device__ __forceinline__ unsigned xb_ld(unsigned* p)              { return __hip_atomic_load(p, __ATOMIC_RELAXED, __HIP_MEMORY_SCOPE_AGENT); }
; __device__ __forceinline__ unsigned xb_add(unsigned* p, unsigned v) { return __hip_atomic_fetch_add(p, v, __ATOMIC_RELAXED, __HIP_MEMORY_SCOPE_AGENT); }
; #define XB_SPIN(cond, bar) do { unsigned _sp = 0; while (cond) { __builtin_amdgcn_s_sleep(1); \
;     if ((++_sp & 255u) == 0u) { if (xb_ld(&(bar)[XB_TMO])) break; if (_sp > XB_SPIN_CAP) { atomicAdd(&(bar)[XB_TMO], 1u); break; } } } } while (0)
; __device__ __forceinline__ void gsync(const int wvs, LAS unsigned char* lds) {
;     ...
;     if (old + 1u == (gen + 1u) * nloc) {
;       __builtin_amdgcn_fence(__ATOMIC_RELEASE, "agent");
;       asm volatile("s_waitcnt vmcnt(0)" ::: "memory");
;       const unsigned og = xb_add(&bar[XB_TOP], 1u);
;       const unsigned tg = og / nx;
;       if (og + 1u == (tg + 1u) * nx) xb_add(&bar[XB_TOPGEN], 1u);
;       else XB_SPIN(xb_ld(&bar[XB_TOPGEN]) == tg, bar);
;       __builtin_amdgcn_fence(__ATOMIC_ACQUIRE, "agent");
;       xb_add(&bar[XB_XGEN(x)], 1u);
;       asm volatile("s_waitcnt vmcnt(0)" ::: "memory");
.LBB0_1578:
	s_or_b64 exec, exec, s[8:9]
	s_mov_b64 s[8:9], exec
	v_mbcnt_lo_u32_b32 v0, s8, 0
	v_mbcnt_hi_u32_b32 v0, s9, v0
	v_cmp_eq_u32_e32 vcc, 0, v0
	s_waitcnt vmcnt(0)
	buffer_inv sc1
	s_and_saveexec_b64 s[12:13], vcc
	s_cbranch_execz .LBB0_1580
	s_bcnt1_i32_b64 s2, s[8:9]
	v_mov_b32_e32 v0, s2
.LBB0_1580:
	s_or_b64 exec, exec, s[12:13]
	s_waitcnt vmcnt(0)

; __device__ __forceinline__ unsigned xb_ld(unsigned* p)              { return __hip_atomic_load(p, __ATOMIC_RELAXED, __HIP_MEMORY_SCOPE_AGENT); }
; __device__ __forceinline__ unsigned xb_add(unsigned* p, unsigned v) { return __hip_atomic_fetch_add(p, v, __ATOMIC_RELAXED, __HIP_MEMORY_SCOPE_AGENT); }
; #define XB_SPIN(cond, bar) do { unsigned _sp = 0; while (cond) { __builtin_amdgcn_s_sleep(1); \
;     if ((++_sp & 255u) == 0u) { if (xb_ld(&(bar)[XB_TMO])) break; if (_sp > XB_SPIN_CAP) { atomicAdd(&(bar)[XB_TMO], 1u); break; } } } } while (0)
; __device__ __forceinline__ void gsync(const int wvs, LAS unsigned char* lds) {
;     ...
;     if (old + 1u == (gen + 1u) * nloc) {
;       __builtin_amdgcn_fence(__ATOMIC_RELEASE, "agent");
;       asm volatile("s_waitcnt vmcnt(0)" ::: "memory");
;       const unsigned og = xb_add(&bar[XB_TOP], 1u);
;       const unsigned tg = og / nx;
;       if (og + 1u == (tg + 1u) * nx) xb_add(&bar[XB_TOPGEN], 1u);
;       else XB_SPIN(xb_ld(&bar[XB_TOPGEN]) == tg, bar);
;       __builtin_amdgcn_fence(__ATOMIC_ACQUIRE, "agent");
;       xb_add(&bar[XB_XGEN(x)], 1u);
;       asm volatile("s_waitcnt vmcnt(0)" ::: "memory");
.LBB0_1787:
	s_or_b64 exec, exec, s[8:9]
	s_mov_b64 s[8:9], exec
	v_mbcnt_lo_u32_b32 v0, s8, 0
	v_mbcnt_hi_u32_b32 v0, s9, v0
	v_cmp_eq_u32_e32 vcc, 0, v0
	s_waitcnt vmcnt(0)
	buffer_inv sc1
	s_and_saveexec_b64 s[12:13], vcc
	s_cbranch_execz .LBB0_1789
	s_bcnt1_i32_b64 s2, s[8:9]
	v_mov_b32_e32 v0, s2
.LBB0_1789:
	s_or_b64 exec, exec, s[12:13]
	s_waitcnt vmcnt(0)

; __device__ __forceinline__ unsigned xb_ld(unsigned* p)              { return __hip_atomic_load(p, __ATOMIC_RELAXED, __HIP_MEMORY_SCOPE_AGENT); }
; __device__ __forceinline__ unsigned xb_add(unsigned* p, unsigned v) { return __hip_atomic_fetch_add(p, v, __ATOMIC_RELAXED, __HIP_MEMORY_SCOPE_AGENT); }
; #define XB_SPIN(cond, bar) do { unsigned _sp = 0; while (cond) { __builtin_amdgcn_s_sleep(1); \
;     if ((++_sp & 255u) == 0u) { if (xb_ld(&(bar)[XB_TMO])) break; if (_sp > XB_SPIN_CAP) { atomicAdd(&(bar)[XB_TMO], 1u); break; } } } } while (0)
; __device__ __forceinline__ void gsync(const int wvs, LAS unsigned char* lds) {
;     ...
;     unsigned nloc = st[0], nx = st[1];
;     if (nloc == 0u) { xcd_complete(bar, x, nloc, nx); st[0] = nloc; st[1] = nx; }
;     const unsigned old = xb_add(&bar[XB_XSUB(x)], 1u);
;     const unsigned gen = old / nloc;
;     if (old + 1u == (gen + 1u) * nloc) {
;       __builtin_amdgcn_fence(__ATOMIC_RELEASE, "agent");
;       asm volatile("s_waitcnt vmcnt(0)" ::: "memory");
;       const unsigned og = xb_add(&bar[XB_TOP], 1u);
;       const unsigned tg = og / nx;
;       if (og + 1u == (tg + 1u) * nx) xb_add(&bar[XB_TOPGEN], 1u);
;       else XB_SPIN(xb_ld(&bar[XB_TOPGEN]) == tg, bar);
;       __builtin_amdgcn_fence(__ATOMIC_ACQUIRE, "agent");
;       xb_add(&bar[XB_XGEN(x)], 1u);
;       asm volatile("s_waitcnt vmcnt(0)" ::: "memory");
;     } else {
;       XB_SPIN(xb_ld(&bar[XB_XGEN(x)]) == gen, bar);
.LBB0_1823:
	s_or_b64 exec, exec, s[12:13]
	v_cvt_f32_u32_e32 v5, v3
	s_waitcnt vmcnt(0)
	v_readfirstlane_b32 s4, v4
	v_sub_u32_e32 v4, 0, v3
	v_rcp_iflag_f32_e32 v5, v5
	v_add_u32_e32 v6, s4, v0
	v_mul_f32_e32 v5, 0x4f7ffffe, v5
	v_cvt_u32_f32_e32 v5, v5
	v_mul_lo_u32 v0, v4, v5
	v_mul_hi_u32 v0, v5, v0
	v_add_u32_e32 v0, v5, v0
	v_mul_hi_u32 v0, v6, v0
	v_mul_lo_u32 v4, v0, v3
	v_sub_u32_e32 v4, v6, v4
	v_add_u32_e32 v5, 1, v0
	v_cmp_ge_u32_e32 vcc, v4, v3
	s_nop 1
	v_cndmask_b32_e32 v0, v0, v5, vcc
	v_sub_u32_e32 v5, v4, v3
	v_cndmask_b32_e32 v4, v4, v5, vcc
	v_add_u32_e32 v5, 1, v0
	v_cmp_ge_u32_e32 vcc, v4, v3
	v_add_u32_e32 v4, 1, v6
	s_nop 0
	v_cndmask_b32_e32 v0, v0, v5, vcc
	v_mul_lo_u32 v5, v3, v0
	v_add_u32_e32 v3, v5, v3
	v_cmp_ne_u32_e32 vcc, v4, v3
	s_and_saveexec_b64 s[4:5], vcc
	s_xor_b64 s[10:11], exec, s[4:5]
	s_cbranch_execz .LBB0_1837
	s_waitcnt lgkmcnt(0)
	s_add_u32 s16, s6, 0xffff500
	s_addc_u32 s17, s7, 0
	v_mov_b32_e32 v2, 0
	global_load_dword v2, v2, s[16:17] sc1
	s_waitcnt vmcnt(0)
	v_cmp_eq_u32_e32 vcc, v2, v0
	s_and_saveexec_b64 s[12:13], vcc
	s_cbranch_execz .LBB0_1836
	s_add_u32 s14, s6, 0xfffc200
	s_addc_u32 s15, s7, 0
	s_mov_b32 s4, 1
	s_mov_b64 s[18:19], 0
	s_branch .LBB0_1827

; __device__ __forceinline__ unsigned xb_ld(unsigned* p)              { return __hip_atomic_load(p, __ATOMIC_RELAXED, __HIP_MEMORY_SCOPE_AGENT); }
; __device__ __forceinline__ unsigned xb_add(unsigned* p, unsigned v) { return __hip_atomic_fetch_add(p, v, __ATOMIC_RELAXED, __HIP_MEMORY_SCOPE_AGENT); }
; #define XB_SPIN(cond, bar) do { unsigned _sp = 0; while (cond) { __builtin_amdgcn_s_sleep(1); \
;     if ((++_sp & 255u) == 0u) { if (xb_ld(&(bar)[XB_TMO])) break; if (_sp > XB_SPIN_CAP) { atomicAdd(&(bar)[XB_TMO], 1u); break; } } } } while (0)
; __device__ __forceinline__ void gsync(const int wvs, LAS unsigned char* lds) {
;     ...
;     if (old + 1u == (gen + 1u) * nloc) {
;       __builtin_amdgcn_fence(__ATOMIC_RELEASE, "agent");
;       asm volatile("s_waitcnt vmcnt(0)" ::: "memory");
;       const unsigned og = xb_add(&bar[XB_TOP], 1u);
;       const unsigned tg = og / nx;
;       if (og + 1u == (tg + 1u) * nx) xb_add(&bar[XB_TOPGEN], 1u);
;       else XB_SPIN(xb_ld(&bar[XB_TOPGEN]) == tg, bar);
;       __builtin_amdgcn_fence(__ATOMIC_ACQUIRE, "agent");
;       xb_add(&bar[XB_XGEN(x)], 1u);
;       asm volatile("s_waitcnt vmcnt(0)" ::: "memory");
.LBB0_1854:
	s_or_b64 exec, exec, s[6:7]
	s_mov_b64 s[6:7], exec
	v_mbcnt_lo_u32_b32 v0, s6, 0
	v_mbcnt_hi_u32_b32 v0, s7, v0
	v_cmp_eq_u32_e32 vcc, 0, v0
	s_waitcnt vmcnt(0)
	buffer_inv sc1
	s_and_saveexec_b64 s[10:11], vcc
	s_cbranch_execz .LBB0_1856
	s_bcnt1_i32_b64 s4, s[6:7]
	v_mov_b32_e32 v0, s4
.LBB0_1856:
	s_or_b64 exec, exec, s[10:11]
	s_waitcnt vmcnt(0)

; __device__ __forceinline__ unsigned xb_ld(unsigned* p)              { return __hip_atomic_load(p, __ATOMIC_RELAXED, __HIP_MEMORY_SCOPE_AGENT); }
; __device__ __forceinline__ unsigned xb_add(unsigned* p, unsigned v) { return __hip_atomic_fetch_add(p, v, __ATOMIC_RELAXED, __HIP_MEMORY_SCOPE_AGENT); }
; #define XB_SPIN(cond, bar) do { unsigned _sp = 0; while (cond) { __builtin_amdgcn_s_sleep(1); \
;     if ((++_sp & 255u) == 0u) { if (xb_ld(&(bar)[XB_TMO])) break; if (_sp > XB_SPIN_CAP) { atomicAdd(&(bar)[XB_TMO], 1u); break; } } } } while (0)
; __device__ __forceinline__ void gsync(const int wvs, LAS unsigned char* lds) {
;     ...
;     unsigned nloc = st[0], nx = st[1];
;     if (nloc == 0u) { xcd_complete(bar, x, nloc, nx); st[0] = nloc; st[1] = nx; }
;     const unsigned old = xb_add(&bar[XB_XSUB(x)], 1u);
;     const unsigned gen = old / nloc;
;     if (old + 1u == (gen + 1u) * nloc) {
;       __builtin_amdgcn_fence(__ATOMIC_RELEASE, "agent");
;       asm volatile("s_waitcnt vmcnt(0)" ::: "memory");
;       const unsigned og = xb_add(&bar[XB_TOP], 1u);
;       const unsigned tg = og / nx;
;       if (og + 1u == (tg + 1u) * nx) xb_add(&bar[XB_TOPGEN], 1u);
;       else XB_SPIN(xb_ld(&bar[XB_TOPGEN]) == tg, bar);
;       __builtin_amdgcn_fence(__ATOMIC_ACQUIRE, "agent");
;       xb_add(&bar[XB_XGEN(x)], 1u);
;       asm volatile("s_waitcnt vmcnt(0)" ::: "memory");
;     } else {
;       XB_SPIN(xb_ld(&bar[XB_XGEN(x)]) == gen, bar);
.LBB0_1917:
	s_or_b64 exec, exec, s[10:11]
	v_cvt_f32_u32_e32 v5, v3
	s_waitcnt vmcnt(0)
	v_readfirstlane_b32 s8, v4
	v_sub_u32_e32 v4, 0, v3
	v_rcp_iflag_f32_e32 v5, v5
	v_add_u32_e32 v6, s8, v0
	v_mul_f32_e32 v5, 0x4f7ffffe, v5
	v_cvt_u32_f32_e32 v5, v5
	v_mul_lo_u32 v0, v4, v5
	v_mul_hi_u32 v0, v5, v0
	v_add_u32_e32 v0, v5, v0
	v_mul_hi_u32 v0, v6, v0
	v_mul_lo_u32 v4, v0, v3
	v_sub_u32_e32 v4, v6, v4
	v_add_u32_e32 v5, 1, v0
	v_cmp_ge_u32_e32 vcc, v4, v3
	s_nop 1
	v_cndmask_b32_e32 v0, v0, v5, vcc
	v_sub_u32_e32 v5, v4, v3
	v_cndmask_b32_e32 v4, v4, v5, vcc
	v_add_u32_e32 v5, 1, v0
	v_cmp_ge_u32_e32 vcc, v4, v3
	v_add_u32_e32 v4, 1, v6
	s_nop 0
	v_cndmask_b32_e32 v0, v0, v5, vcc
	v_mul_lo_u32 v5, v3, v0
	v_add_u32_e32 v3, v5, v3
	v_cmp_ne_u32_e32 vcc, v4, v3
	s_and_saveexec_b64 s[8:9], vcc
	s_xor_b64 s[8:9], exec, s[8:9]
	s_cbranch_execz .LBB0_1931
	s_waitcnt lgkmcnt(0)
	s_add_u32 s14, s4, 0xffff500
	s_addc_u32 s15, s5, 0
	v_mov_b32_e32 v2, 0
	global_load_dword v2, v2, s[14:15] sc1
	s_waitcnt vmcnt(0)
	v_cmp_eq_u32_e32 vcc, v2, v0
	s_and_saveexec_b64 s[10:11], vcc
	s_cbranch_execz .LBB0_1930
	s_add_u32 s12, s4, 0xfffc200
	s_addc_u32 s13, s5, 0
	s_mov_b32 s26, 1
	s_mov_b64 s[16:17], 0
	s_branch .LBB0_1921

; __device__ __forceinline__ unsigned xb_ld(unsigned* p)              { return __hip_atomic_load(p, __ATOMIC_RELAXED, __HIP_MEMORY_SCOPE_AGENT); }
; __device__ __forceinline__ unsigned xb_add(unsigned* p, unsigned v) { return __hip_atomic_fetch_add(p, v, __ATOMIC_RELAXED, __HIP_MEMORY_SCOPE_AGENT); }
; #define XB_SPIN(cond, bar) do { unsigned _sp = 0; while (cond) { __builtin_amdgcn_s_sleep(1); \
;     if ((++_sp & 255u) == 0u) { if (xb_ld(&(bar)[XB_TMO])) break; if (_sp > XB_SPIN_CAP) { atomicAdd(&(bar)[XB_TMO], 1u); break; } } } } while (0)
; __device__ __forceinline__ void gsync(const int wvs, LAS unsigned char* lds) {
;     ...
;     if (old + 1u == (gen + 1u) * nloc) {
;       __builtin_amdgcn_fence(__ATOMIC_RELEASE, "agent");
;       asm volatile("s_waitcnt vmcnt(0)" ::: "memory");
;       const unsigned og = xb_add(&bar[XB_TOP], 1u);
;       const unsigned tg = og / nx;
;       if (og + 1u == (tg + 1u) * nx) xb_add(&bar[XB_TOPGEN], 1u);
;       else XB_SPIN(xb_ld(&bar[XB_TOPGEN]) == tg, bar);
;       __builtin_amdgcn_fence(__ATOMIC_ACQUIRE, "agent");
;       xb_add(&bar[XB_XGEN(x)], 1u);
;       asm volatile("s_waitcnt vmcnt(0)" ::: "memory");
.LBB0_1949:
	s_bcnt1_i32_b64 s4, s[4:5]
	v_mov_b32_e32 v0, s4
	s_getpc_b64 s[98:99]
